# NA cache-conversion tiles (ph13 tail on 64 blocks): 32 row loads in flight instead of a load-wait-store chain per row
# speedup vs baseline: 1.0076x; 1.0074x over previous
.LBB0_1269:
	s_load_dwordx4 s[68:71], s[0:1], 0x20
	s_load_dwordx4 s[72:75], s[0:1], 0x168
	s_sub_u32 s84, s64, 0x800
	s_lshr_b32 s85, s84, 4
	s_and_b32 s86, s84, 15
	s_lshl_b32 s86, s86, 4
	v_and_b32_e32 v230, 0x3ff, v0
	s_lshl_b32 s87, s85, 8
	s_add_u32 s87, s87, s86
	s_lshl_b32 s88, s87, 12
	v_lshl_add_u32 v231, v230, 4, s88
	s_mul_i32 s89, s85, 0x900
	s_add_u32 s89, s89, 0x1000
	s_add_u32 s89, s89, s86
	s_lshl_b32 s89, s89, 11
	v_lshl_add_u32 v232, v230, 3, s89
	s_mul_i32 s90, s85, 0x480000
	s_add_u32 s90, s90, 0x800000
	s_lshl_b32 s86, s86, 1
	s_add_u32 s90, s90, s86
	v_mul_u32_u24_e32 v233, 0x4800, v230
	v_add_u32_e32 v233, s90, v233
	s_waitcnt lgkmcnt(0)
	global_load_dwordx4 v[2:5], v231, s[68:69] nt
	global_load_dwordx4 v[66:69], v231, s[70:71] nt
	s_add_u32 s68, s68, 0x1000
	s_addc_u32 s69, s69, 0
	s_add_u32 s70, s70, 0x1000
	s_addc_u32 s71, s71, 0
	global_load_dwordx4 v[6:9], v231, s[68:69] nt
	global_load_dwordx4 v[70:73], v231, s[70:71] nt
	s_add_u32 s68, s68, 0x1000
	s_addc_u32 s69, s69, 0
	s_add_u32 s70, s70, 0x1000
	s_addc_u32 s71, s71, 0
	global_load_dwordx4 v[10:13], v231, s[68:69] nt
	global_load_dwordx4 v[74:77], v231, s[70:71] nt
	s_add_u32 s68, s68, 0x1000
	s_addc_u32 s69, s69, 0
	s_add_u32 s70, s70, 0x1000
	s_addc_u32 s71, s71, 0
	global_load_dwordx4 v[14:17], v231, s[68:69] nt
	global_load_dwordx4 v[78:81], v231, s[70:71] nt
	s_add_u32 s68, s68, 0x1000
	s_addc_u32 s69, s69, 0
	s_add_u32 s70, s70, 0x1000
	s_addc_u32 s71, s71, 0
	global_load_dwordx4 v[18:21], v231, s[68:69] nt
	global_load_dwordx4 v[82:85], v231, s[70:71] nt
	s_add_u32 s68, s68, 0x1000
	s_addc_u32 s69, s69, 0
	s_add_u32 s70, s70, 0x1000
	s_addc_u32 s71, s71, 0
	global_load_dwordx4 v[22:25], v231, s[68:69] nt
	global_load_dwordx4 v[86:89], v231, s[70:71] nt
	s_add_u32 s68, s68, 0x1000
	s_addc_u32 s69, s69, 0
	s_add_u32 s70, s70, 0x1000
	s_addc_u32 s71, s71, 0
	global_load_dwordx4 v[26:29], v231, s[68:69] nt
	global_load_dwordx4 v[90:93], v231, s[70:71] nt
	s_add_u32 s68, s68, 0x1000
	s_addc_u32 s69, s69, 0
	s_add_u32 s70, s70, 0x1000
	s_addc_u32 s71, s71, 0
	global_load_dwordx4 v[30:33], v231, s[68:69] nt
	global_load_dwordx4 v[94:97], v231, s[70:71] nt
	s_add_u32 s68, s68, 0x1000
	s_addc_u32 s69, s69, 0
	s_add_u32 s70, s70, 0x1000
	s_addc_u32 s71, s71, 0
	global_load_dwordx4 v[34:37], v231, s[68:69] nt
	global_load_dwordx4 v[198:201], v231, s[70:71] nt
	s_add_u32 s68, s68, 0x1000
	s_addc_u32 s69, s69, 0
	s_add_u32 s70, s70, 0x1000
	s_addc_u32 s71, s71, 0
	global_load_dwordx4 v[38:41], v231, s[68:69] nt
	global_load_dwordx4 v[202:205], v231, s[70:71] nt
	s_add_u32 s68, s68, 0x1000
	s_addc_u32 s69, s69, 0
	s_add_u32 s70, s70, 0x1000
	s_addc_u32 s71, s71, 0
	global_load_dwordx4 v[42:45], v231, s[68:69] nt
	global_load_dwordx4 v[206:209], v231, s[70:71] nt
	s_add_u32 s68, s68, 0x1000
	s_addc_u32 s69, s69, 0
	s_add_u32 s70, s70, 0x1000
	s_addc_u32 s71, s71, 0
	global_load_dwordx4 v[46:49], v231, s[68:69] nt
	global_load_dwordx4 v[210:213], v231, s[70:71] nt
	s_add_u32 s68, s68, 0x1000
	s_addc_u32 s69, s69, 0
	s_add_u32 s70, s70, 0x1000
	s_addc_u32 s71, s71, 0
	global_load_dwordx4 v[50:53], v231, s[68:69] nt
	global_load_dwordx4 v[214:217], v231, s[70:71] nt
	s_add_u32 s68, s68, 0x1000
	s_addc_u32 s69, s69, 0
	s_add_u32 s70, s70, 0x1000
	s_addc_u32 s71, s71, 0
	global_load_dwordx4 v[54:57], v231, s[68:69] nt
	global_load_dwordx4 v[218:221], v231, s[70:71] nt
	s_add_u32 s68, s68, 0x1000
	s_addc_u32 s69, s69, 0
	s_add_u32 s70, s70, 0x1000
	s_addc_u32 s71, s71, 0
	global_load_dwordx4 v[58:61], v231, s[68:69] nt
	global_load_dwordx4 v[222:225], v231, s[70:71] nt
	s_add_u32 s68, s68, 0x1000
	s_addc_u32 s69, s69, 0
	s_add_u32 s70, s70, 0x1000
	s_addc_u32 s71, s71, 0
	global_load_dwordx4 v[62:65], v231, s[68:69] nt
	global_load_dwordx4 v[226:229], v231, s[70:71] nt
	s_waitcnt vmcnt(31)
	v_cvt_pk_bf16_f32 v2, v2, v3
	v_cvt_pk_bf16_f32 v3, v4, v5
	global_store_dwordx2 v232, v[2:3], s[72:73]
	s_add_u32 s72, s72, 0x800
	s_addc_u32 s73, s73, 0
	s_waitcnt vmcnt(30)
	v_cvt_pk_bf16_f32 v6, v6, v7
	v_cvt_pk_bf16_f32 v7, v8, v9
	global_store_dwordx2 v232, v[6:7], s[72:73]
	s_add_u32 s72, s72, 0x800
	s_addc_u32 s73, s73, 0
	s_waitcnt vmcnt(29)
	v_cvt_pk_bf16_f32 v10, v10, v11
	v_cvt_pk_bf16_f32 v11, v12, v13
	global_store_dwordx2 v232, v[10:11], s[72:73]
	s_add_u32 s72, s72, 0x800
	s_addc_u32 s73, s73, 0
	s_waitcnt vmcnt(28)
	v_cvt_pk_bf16_f32 v14, v14, v15
	v_cvt_pk_bf16_f32 v15, v16, v17
	global_store_dwordx2 v232, v[14:15], s[72:73]
	s_add_u32 s72, s72, 0x800
	s_addc_u32 s73, s73, 0
	s_waitcnt vmcnt(27)
	v_cvt_pk_bf16_f32 v18, v18, v19
	v_cvt_pk_bf16_f32 v19, v20, v21
	global_store_dwordx2 v232, v[18:19], s[72:73]
	s_add_u32 s72, s72, 0x800
	s_addc_u32 s73, s73, 0
	s_waitcnt vmcnt(26)
	v_cvt_pk_bf16_f32 v22, v22, v23
	v_cvt_pk_bf16_f32 v23, v24, v25
	global_store_dwordx2 v232, v[22:23], s[72:73]
	s_add_u32 s72, s72, 0x800
	s_addc_u32 s73, s73, 0
	s_waitcnt vmcnt(25)
	v_cvt_pk_bf16_f32 v26, v26, v27
	v_cvt_pk_bf16_f32 v27, v28, v29
	global_store_dwordx2 v232, v[26:27], s[72:73]
	s_add_u32 s72, s72, 0x800
	s_addc_u32 s73, s73, 0
	s_waitcnt vmcnt(24)
	v_cvt_pk_bf16_f32 v30, v30, v31
	v_cvt_pk_bf16_f32 v31, v32, v33
	global_store_dwordx2 v232, v[30:31], s[72:73]
	s_add_u32 s72, s72, 0x800
	s_addc_u32 s73, s73, 0
	s_waitcnt vmcnt(23)
	v_cvt_pk_bf16_f32 v34, v34, v35
	v_cvt_pk_bf16_f32 v35, v36, v37
	global_store_dwordx2 v232, v[34:35], s[72:73]
	s_add_u32 s72, s72, 0x800
	s_addc_u32 s73, s73, 0
	s_waitcnt vmcnt(22)
	v_cvt_pk_bf16_f32 v38, v38, v39
	v_cvt_pk_bf16_f32 v39, v40, v41
	global_store_dwordx2 v232, v[38:39], s[72:73]
	s_add_u32 s72, s72, 0x800
	s_addc_u32 s73, s73, 0
	s_waitcnt vmcnt(21)
	v_cvt_pk_bf16_f32 v42, v42, v43
	v_cvt_pk_bf16_f32 v43, v44, v45
	global_store_dwordx2 v232, v[42:43], s[72:73]
	s_add_u32 s72, s72, 0x800
	s_addc_u32 s73, s73, 0
	s_waitcnt vmcnt(20)
	v_cvt_pk_bf16_f32 v46, v46, v47
	v_cvt_pk_bf16_f32 v47, v48, v49
	global_store_dwordx2 v232, v[46:47], s[72:73]
	s_add_u32 s72, s72, 0x800
	s_addc_u32 s73, s73, 0
	s_waitcnt vmcnt(19)
	v_cvt_pk_bf16_f32 v50, v50, v51
	v_cvt_pk_bf16_f32 v51, v52, v53
	global_store_dwordx2 v232, v[50:51], s[72:73]
	s_add_u32 s72, s72, 0x800
	s_addc_u32 s73, s73, 0
	s_waitcnt vmcnt(18)
	v_cvt_pk_bf16_f32 v54, v54, v55
	v_cvt_pk_bf16_f32 v55, v56, v57
	global_store_dwordx2 v232, v[54:55], s[72:73]
	s_add_u32 s72, s72, 0x800
	s_addc_u32 s73, s73, 0
	s_waitcnt vmcnt(17)
	v_cvt_pk_bf16_f32 v58, v58, v59
	v_cvt_pk_bf16_f32 v59, v60, v61
	global_store_dwordx2 v232, v[58:59], s[72:73]
	s_add_u32 s72, s72, 0x800
	s_addc_u32 s73, s73, 0
	s_waitcnt vmcnt(16)
	v_cvt_pk_bf16_f32 v62, v62, v63
	v_cvt_pk_bf16_f32 v63, v64, v65
	global_store_dwordx2 v232, v[62:63], s[72:73]
	s_waitcnt vmcnt(16)
	v_cvt_pk_bf16_f32 v236, v66, v70
	v_cvt_pk_bf16_f32 v237, v74, v78
	v_cvt_pk_bf16_f32 v238, v82, v86
	v_cvt_pk_bf16_f32 v239, v90, v94
	v_cvt_pk_bf16_f32 v240, v198, v202
	v_cvt_pk_bf16_f32 v241, v206, v210
	v_cvt_pk_bf16_f32 v242, v214, v218
	v_cvt_pk_bf16_f32 v243, v222, v226
	global_store_dwordx4 v233, v[236:239], s[74:75]
	global_store_dwordx4 v233, v[240:243], s[74:75] offset:16
	s_add_u32 s74, s74, 0x1200
	s_addc_u32 s75, s75, 0
	s_nop 1
	v_cvt_pk_bf16_f32 v236, v67, v71
	v_cvt_pk_bf16_f32 v237, v75, v79
	v_cvt_pk_bf16_f32 v238, v83, v87
	v_cvt_pk_bf16_f32 v239, v91, v95
	v_cvt_pk_bf16_f32 v240, v199, v203
	v_cvt_pk_bf16_f32 v241, v207, v211
	v_cvt_pk_bf16_f32 v242, v215, v219
	v_cvt_pk_bf16_f32 v243, v223, v227
	global_store_dwordx4 v233, v[236:239], s[74:75]
	global_store_dwordx4 v233, v[240:243], s[74:75] offset:16
	s_add_u32 s74, s74, 0x1200
	s_addc_u32 s75, s75, 0
	s_nop 1
	v_cvt_pk_bf16_f32 v236, v68, v72
	v_cvt_pk_bf16_f32 v237, v76, v80
	v_cvt_pk_bf16_f32 v238, v84, v88
	v_cvt_pk_bf16_f32 v239, v92, v96
	v_cvt_pk_bf16_f32 v240, v200, v204
	v_cvt_pk_bf16_f32 v241, v208, v212
	v_cvt_pk_bf16_f32 v242, v216, v220
	v_cvt_pk_bf16_f32 v243, v224, v228
	global_store_dwordx4 v233, v[236:239], s[74:75]
	global_store_dwordx4 v233, v[240:243], s[74:75] offset:16
	s_add_u32 s74, s74, 0x1200
	s_addc_u32 s75, s75, 0
	s_nop 1
	v_cvt_pk_bf16_f32 v236, v69, v73
	v_cvt_pk_bf16_f32 v237, v77, v81
	v_cvt_pk_bf16_f32 v238, v85, v89
	v_cvt_pk_bf16_f32 v239, v93, v97
	v_cvt_pk_bf16_f32 v240, v201, v205
	v_cvt_pk_bf16_f32 v241, v209, v213
	v_cvt_pk_bf16_f32 v242, v217, v221
	v_cvt_pk_bf16_f32 v243, v225, v229
	global_store_dwordx4 v233, v[236:239], s[74:75]
	global_store_dwordx4 v233, v[240:243], s[74:75] offset:16
	s_branch .LBB0_1266
